# adds: attention chunk loop unrolled x2 with K-fragment register ping-pong (no copies), 32-bit LDS address mad, shared V base offsets
# baseline (speedup 1.0000x reference)
; #define LAS __attribute__((address_space(3)))
; __device__ __forceinline__ void attn_phase(LAS unsigned char* lds, const bf16_t* Q, const bf16_t* Kb, const bf16_t* Vt, bf16_t* AO, const float* sink, const float* qg, const float* kg) {
;     ...
;             for (int cc = 0; cc < 9; ++cc) {
;                 const int kw0 = q0 + 32 * cc, l0 = nb * 128 - 128 + kw0;
;                 const bool valid = (l0 >= 0 && l0 < SEQ);
;                 u32x2 vv[2][2][2]; bf16x8 kn[4];
; #pragma unroll
;                 for (int st = 0; st < 2; ++st)
; #pragma unroll
;                     for (int dt = 0; dt < 2; ++dt) { const LAS unsigned char* vp = Vl + (32 * dt + r) * VROW + (kw0 + 16 * st + 4 * h) * 2; vv[st][dt][0] = *(const LAS u32x2*)vp; vv[st][dt][1] = *(const LAS u32x2*)(vp + 16); }
;                 const int kwn = cc < 8 ? kw0 + 32 : kw0;
; #pragma unroll
;                 for (int st = 0; st < 4; ++st) kn[st] = *(const LAS bf16x8*)(Kl + (kwn + r) * KROW + (16 * st + 8 * h) * 2);
;                 __builtin_amdgcn_sched_barrier(0);
;                 if (valid) {
;                 f32x16 sc;
; #pragma unroll
;                 for (int e = 0; e < 16; ++e) sc[e] = -MREF;
; #pragma unroll
;                 for (int st = 0; st < 4; ++st) sc = __builtin_amdgcn_mfma_f32_32x32x16_bf16(kf[st], qf[st], sc, 0, 0, 0);
;                 if (cc == 0) {
; #pragma unroll
;                     for (int e = 0; e < 16; ++e) { const int kj = (e & 3) + 8 * (e >> 2) + 4 * h; if (kj < r) sc[e] = -INFINITY; }
;                 }
;                 if (cc == 8) {
; #pragma unroll
;                     for (int e = 0; e < 16; ++e) { const int kj = (e & 3) + 8 * (e >> 2) + 4 * h; if (kj > r) sc[e] = -INFINITY; }
.LBB0_181:
	s_add_i32 s0, s17, 0x80
	s_add_i32 s1, s15, s17
	s_add_i32 s30, s17, 0xa0
	s_cmpk_eq_i32 s16, 0x1c0
	s_cselect_b64 vcc, -1, 0
	v_add_u32_e32 v0, s16, v246
	s_and_b64 s[12:13], vcc, exec
	v_add_u32_e32 v2, 0xd800, v0
	v_add_u32_e32 v6, 0x13940, v0
	s_cselect_b32 s0, s0, s30
	ds_read2_b64 v[192:195], v2 offset0:8 offset1:10
	ds_read2_b64 v[2:5], v2 offset0:12 offset1:14
	ds_read_b64 v[10:11], v6
	ds_read_b64 v[12:13], v6 offset:16
	ds_read_b64 v[8:9], v6 offset:48
	ds_read_b64 v[6:7], v6 offset:32
	v_or_b32_e32 v0, s0, v214
	v_mad_u32_u24 v14, v0, s18, v198
	ds_read_b128 v[64:67], v14
	ds_read_b128 v[68:71], v14 offset:32
	ds_read_b128 v[72:75], v14 offset:64
	ds_read_b128 v[76:79], v14 offset:96
	s_cmpk_gt_u32 s1, 0xfff
	s_cbranch_scc1 .LBB0_185
	s_waitcnt vmcnt(3) lgkmcnt(13)
	v_mfma_f32_32x32x16_bf16 v[96:111], v[80:83], v[188:191], v[16:31]
	s_andn2_b64 vcc, exec, vcc
	s_waitcnt vmcnt(2) lgkmcnt(12)
	v_mfma_f32_32x32x16_bf16 v[96:111], v[84:87], v[184:187], v[96:111]
	s_waitcnt vmcnt(1) lgkmcnt(11)
	v_mfma_f32_32x32x16_bf16 v[96:111], v[88:91], v[180:183], v[96:111]
	s_waitcnt vmcnt(0) lgkmcnt(10)
	v_mfma_f32_32x32x16_bf16 v[96:111], v[92:95], v[176:179], v[96:111]
	s_cbranch_vccnz .LBB0_184
	s_nop 10
	v_cndmask_b32_e64 v0, v96, v235, s[72:73]
	v_cndmask_b32_e64 v97, v235, v97, s[38:39]
	v_cndmask_b32_e64 v96, v0, v96, s[38:39]
	v_cndmask_b32_e64 v98, v98, v235, s[74:75]
	v_cndmask_b32_e64 v99, v99, v235, s[76:77]
	v_cndmask_b32_e64 v100, v100, v235, s[78:79]
	v_cndmask_b32_e64 v101, v101, v235, s[80:81]
	v_cndmask_b32_e64 v102, v102, v235, s[82:83]
	v_cndmask_b32_e64 v103, v103, v235, s[84:85]
	v_cndmask_b32_e64 v104, v104, v235, s[86:87]
	v_cndmask_b32_e64 v105, v105, v235, s[88:89]
	v_cndmask_b32_e64 v106, v106, v235, s[90:91]
	v_cndmask_b32_e64 v107, v107, v235, s[92:93]
	v_cndmask_b32_e64 v108, v108, v235, s[94:95]
	v_cndmask_b32_e64 v109, v109, v235, s[96:97]
	v_cndmask_b32_e64 v110, v110, v235, s[36:37]
	v_cndmask_b32_e64 v111, v111, v235, s[4:5]

; #define LAS __attribute__((address_space(3)))
; __device__ __forceinline__ void attn_phase(LAS unsigned char* lds, const bf16_t* Q, const bf16_t* Kb, const bf16_t* Vt, bf16_t* AO, const float* sink, const float* qg, const float* kg) {
;     ...
;             for (int cc = 0; cc < 9; ++cc) {
;                 const int kw0 = q0 + 32 * cc, l0 = nb * 128 - 128 + kw0;
;                 const bool valid = (l0 >= 0 && l0 < SEQ);
;                 u32x2 vv[2][2][2]; bf16x8 kn[4];
; #pragma unroll
;                 for (int st = 0; st < 2; ++st)
; #pragma unroll
;                     for (int dt = 0; dt < 2; ++dt) { const LAS unsigned char* vp = Vl + (32 * dt + r) * VROW + (kw0 + 16 * st + 4 * h) * 2; vv[st][dt][0] = *(const LAS u32x2*)vp; vv[st][dt][1] = *(const LAS u32x2*)(vp + 16); }
;                 const int kwn = cc < 8 ? kw0 + 32 : kw0;
; #pragma unroll
;                 for (int st = 0; st < 4; ++st) kn[st] = *(const LAS bf16x8*)(Kl + (kwn + r) * KROW + (16 * st + 8 * h) * 2);
;                 __builtin_amdgcn_sched_barrier(0);
;                 if (valid) {
;                 f32x16 sc;
; #pragma unroll
;                 for (int e = 0; e < 16; ++e) sc[e] = -MREF;
; #pragma unroll
;                 for (int st = 0; st < 4; ++st) sc = __builtin_amdgcn_mfma_f32_32x32x16_bf16(kf[st], qf[st], sc, 0, 0, 0);
;                 if (cc == 0) {
; #pragma unroll
;                     for (int e = 0; e < 16; ++e) { const int kj = (e & 3) + 8 * (e >> 2) + 4 * h; if (kj < r) sc[e] = -INFINITY; }
;                 }
;                 if (cc == 8) {
; #pragma unroll
;                     for (int e = 0; e < 16; ++e) { const int kj = (e & 3) + 8 * (e >> 2) + 4 * h; if (kj > r) sc[e] = -INFINITY; }
;                 }
;                 float ps = 0.f;
; #pragma unroll
;                 for (int e = 0; e < 16; ++e) { const float pe = __builtin_amdgcn_exp2f(sc[e]); ps += pe; sc[e] = pe; }
;                 lrun += ps;
; #pragma unroll
;                 for (int st = 0; st < 2; ++st) {
;                     u32x4 pw; pw.x = cvt_pk_bf16(sc[8 * st + 0], sc[8 * st + 1]); pw.y = cvt_pk_bf16(sc[8 * st + 2], sc[8 * st + 3]); pw.z = cvt_pk_bf16(sc[8 * st + 4], sc[8 * st + 5]); pw.w = cvt_pk_bf16(sc[8 * st + 6], sc[8 * st + 7]);
;                     const bf16x8 pf = __builtin_bit_cast(bf16x8, pw);
.LBB0_185:
	s_add_i32 s16, s16, 64
	s_add_i32 s17, s17, 32
	s_cmpk_eq_i32 s16, 0x200
	s_cbranch_scc1 .LBB0_187
	s_waitcnt lgkmcnt(0)
	s_add_i32 s0, s17, 0x80
	s_add_i32 s1, s15, s17
	s_add_i32 s30, s17, 0xa0
	s_cmpk_eq_i32 s16, 0x1c0
	s_cselect_b64 vcc, -1, 0
	v_add_u32_e32 v0, s16, v246
	s_and_b64 s[12:13], vcc, exec
	v_add_u32_e32 v2, 0xd800, v0
	v_add_u32_e32 v6, 0x13940, v0
	s_cselect_b32 s0, s0, s30
	ds_read2_b64 v[192:195], v2 offset0:8 offset1:10
	ds_read2_b64 v[2:5], v2 offset0:12 offset1:14
	ds_read_b64 v[10:11], v6
	ds_read_b64 v[12:13], v6 offset:16
	ds_read_b64 v[8:9], v6 offset:48
	ds_read_b64 v[6:7], v6 offset:32
	v_or_b32_e32 v0, s0, v214
	v_mad_u32_u24 v14, v0, s18, v198
	ds_read_b128 v[80:83], v14
	ds_read_b128 v[84:87], v14 offset:32
	ds_read_b128 v[88:91], v14 offset:64
	ds_read_b128 v[92:95], v14 offset:96
	s_cmpk_gt_u32 s1, 0xfff
	s_cbranch_scc1 .Lattn_185b
	s_waitcnt vmcnt(3) lgkmcnt(13)
	v_mfma_f32_32x32x16_bf16 v[96:111], v[64:67], v[188:191], v[16:31]
	s_andn2_b64 vcc, exec, vcc
	s_waitcnt vmcnt(2) lgkmcnt(12)
	v_mfma_f32_32x32x16_bf16 v[96:111], v[68:71], v[184:187], v[96:111]
	s_waitcnt vmcnt(1) lgkmcnt(11)
	v_mfma_f32_32x32x16_bf16 v[96:111], v[72:75], v[180:183], v[96:111]
	s_waitcnt vmcnt(0) lgkmcnt(10)
	v_mfma_f32_32x32x16_bf16 v[96:111], v[76:79], v[176:179], v[96:111]
	s_cbranch_vccnz .Lattn_184b
	s_nop 10
	v_cndmask_b32_e64 v0, v96, v235, s[72:73]
	v_cndmask_b32_e64 v97, v235, v97, s[38:39]
	v_cndmask_b32_e64 v96, v0, v96, s[38:39]
	v_cndmask_b32_e64 v98, v98, v235, s[74:75]
	v_cndmask_b32_e64 v99, v99, v235, s[76:77]
	v_cndmask_b32_e64 v100, v100, v235, s[78:79]
	v_cndmask_b32_e64 v101, v101, v235, s[80:81]
	v_cndmask_b32_e64 v102, v102, v235, s[82:83]
	v_cndmask_b32_e64 v103, v103, v235, s[84:85]
	v_cndmask_b32_e64 v104, v104, v235, s[86:87]
	v_cndmask_b32_e64 v105, v105, v235, s[88:89]
	v_cndmask_b32_e64 v106, v106, v235, s[90:91]
	v_cndmask_b32_e64 v107, v107, v235, s[92:93]
	v_cndmask_b32_e64 v108, v108, v235, s[94:95]
	v_cndmask_b32_e64 v109, v109, v235, s[96:97]
	v_cndmask_b32_e64 v110, v110, v235, s[36:37]
	v_cndmask_b32_e64 v111, v111, v235, s[4:5]
.Lattn_184b:
	s_nop 10
	v_exp_f32_e32 v0, v96
	v_exp_f32_e32 v14, v97
	v_exp_f32_e32 v15, v98
	v_exp_f32_e32 v68, v99
	v_exp_f32_e32 v69, v100
	v_cvt_pk_bf16_f32 v64, v0, v14
	v_add_f32_e32 v0, 0, v0
	v_exp_f32_e32 v70, v101
	v_exp_f32_e32 v71, v102
	v_exp_f32_e32 v72, v103
	v_cvt_pk_bf16_f32 v65, v15, v68
	v_cvt_pk_bf16_f32 v66, v69, v70
	v_cvt_pk_bf16_f32 v67, v71, v72
	v_add_f32_e32 v0, v14, v0
	s_waitcnt lgkmcnt(9)
	v_mfma_f32_32x32x16_bf16 v[48:63], v[192:195], v[64:67], v[48:63]
	v_add_f32_e32 v0, v15, v0
	v_add_f32_e32 v0, v68, v0
	v_exp_f32_e32 v73, v104
	v_add_f32_e32 v0, v69, v0
	v_exp_f32_e32 v74, v105
	v_add_f32_e32 v0, v70, v0
	v_exp_f32_e32 v75, v106
	s_waitcnt lgkmcnt(6)
	v_mfma_f32_32x32x16_bf16 v[32:47], v[10:13], v[64:67], v[32:47]
	v_add_f32_e32 v0, v71, v0
	v_exp_f32_e32 v76, v107
	v_add_f32_e32 v0, v72, v0
	v_exp_f32_e32 v77, v108
	v_add_f32_e32 v0, v73, v0
	v_exp_f32_e32 v78, v109
	v_exp_f32_e32 v79, v110
	v_exp_f32_e32 v96, v111
	v_cvt_pk_bf16_f32 v10, v73, v74
	v_cvt_pk_bf16_f32 v11, v75, v76
	v_cvt_pk_bf16_f32 v12, v77, v78
	v_cvt_pk_bf16_f32 v13, v79, v96
	v_add_f32_e32 v0, v74, v0
	v_mfma_f32_32x32x16_bf16 v[48:63], v[2:5], v[10:13], v[48:63]
	v_add_f32_e32 v0, v75, v0
	v_add_f32_e32 v0, v76, v0
	v_add_f32_e32 v0, v77, v0
	v_add_f32_e32 v0, v78, v0
	v_add_f32_e32 v0, v79, v0
	v_add_f32_e32 v0, v96, v0
	v_add_f32_e32 v209, v209, v0
	s_waitcnt lgkmcnt(4)
	v_mfma_f32_32x32x16_bf16 v[32:47], v[6:9], v[10:13], v[32:47]
.Lattn_185b:
	s_add_i32 s16, s16, 64
	s_add_i32 s17, s17, 32
	s_cmpk_eq_i32 s16, 0x200
	s_cbranch_scc1 .LBB0_187
	s_waitcnt lgkmcnt(0)
	s_branch .LBB0_181
